# fix: MLA prompt loop per-tile DMA wait counts 6|4 -> 5|3 (V tile issued two tiles earlier is now guaranteed landed before the barrier); otherwise same as previous best
# speedup vs baseline: 1.0018x; 1.0018x over previous
.Lmy_nors_3:
	s_waitcnt lgkmcnt(0)
	v_add_u32_e32 v2, 0x6000, v237
	v_mfma_f32_32x32x16_bf16 v[82:97], v[218:221], v[4:7], v[66:81]
	v_exp_f32_e32 v142, v142
	v_exp_f32_e32 v143, v143
	v_exp_f32_e32 v144, v144
	v_add_f32_e32 v27, v142, v143
	v_exp_f32_e32 v145, v145
	ds_read_b64_tr_b16 v[114:115], v2 offset:49152
	ds_read_b64_tr_b16 v[116:117], v2 offset:49664
	ds_read_b64_tr_b16 v[118:119], v2 offset:50176
	ds_read_b64_tr_b16 v[120:121], v2 offset:50688
	v_mfma_f32_32x32x16_bf16 v[98:113], v[214:217], v[4:7], v[66:81]
	v_exp_f32_e32 v146, v146
	v_add_f32_e32 v27, v27, v144
	v_exp_f32_e32 v147, v147
	v_add_f32_e32 v27, v27, v145
	v_exp_f32_e32 v148, v148
	ds_read_b64_tr_b16 v[122:123], v2 offset:51200
	ds_read_b64_tr_b16 v[124:125], v2 offset:51712
	ds_read_b64_tr_b16 v[126:127], v2 offset:52224
	ds_read_b64_tr_b16 v[128:129], v2 offset:52736
	v_mfma_f32_32x32x16_bf16 v[82:97], v[210:213], v[8:11], v[82:97]
	v_add_f32_e32 v27, v27, v146
	v_exp_f32_e32 v149, v149
	v_add_f32_e32 v27, v27, v147
	v_add_f32_e32 v27, v27, v148
	v_add_f32_e32 v27, v27, v149
	ds_read_b64_tr_b16 v[240:241], v2 offset:53248
	ds_read_b64_tr_b16 v[242:243], v2 offset:53760
	ds_read_b64_tr_b16 v[244:245], v2 offset:54272
	ds_read_b64_tr_b16 v[246:247], v2 offset:54784
	v_mfma_f32_32x32x16_bf16 v[98:113], v[206:209], v[8:11], v[98:113]
	v_cvt_pk_bf16_f32 v142, v142, v143
	v_cvt_pk_bf16_f32 v143, v144, v145
	v_cvt_pk_bf16_f32 v144, v146, v147
	v_cvt_pk_bf16_f32 v145, v148, v149
	ds_read_b64_tr_b16 v[248:249], v2 offset:55296
	ds_read_b64_tr_b16 v[250:251], v2 offset:55808
	ds_read_b64_tr_b16 v[20:21], v2 offset:56320
	ds_read_b64_tr_b16 v[22:23], v2 offset:56832
	v_mfma_f32_32x32x16_bf16 v[82:97], v[202:205], v[12:15], v[82:97]
	v_exp_f32_e32 v150, v150
	v_exp_f32_e32 v151, v151
	v_exp_f32_e32 v152, v152
	v_add_f32_e32 v27, v27, v150
	v_exp_f32_e32 v153, v153
	v_mfma_f32_32x32x16_bf16 v[98:113], v[198:201], v[12:15], v[98:113]
	v_add_f32_e32 v27, v27, v151
	v_exp_f32_e32 v154, v154
	v_add_f32_e32 v27, v27, v152
	v_exp_f32_e32 v155, v155
	v_add_f32_e32 v27, v27, v153
	s_waitcnt vmcnt(5)
	s_barrier
	v_mfma_f32_32x32x16_bf16 v[82:97], v[194:197], v[130:133], v[82:97]
	s_add_u32 m0, s57, 0x4000
	v_exp_f32_e32 v156, v156
	v_add_f32_e32 v27, v27, v154
	global_load_lds_dwordx4 v[28:29], off
	v_lshl_add_u64 v[28:29], v[28:29], 0, s[30:31]
	v_exp_f32_e32 v157, v157
	v_add_f32_e32 v27, v27, v155
	v_add_f32_e32 v27, v27, v156
	v_mfma_f32_32x32x16_bf16 v[98:113], v[190:193], v[130:133], v[98:113]
	s_cmp_eq_u32 s79, 1
	s_cbranch_scc1 .Lmy_gl_4
	s_add_u32 m0, s40, 0x0
	s_nop 0
	global_load_lds_dwordx4 v[24:25], off
	v_lshl_add_u64 v[24:25], v[24:25], 0, s[30:31]

.Lmy_A_loop:
	s_waitcnt lgkmcnt(0)
	v_mov_b32_e32 v2, v237
	v_mfma_f32_32x32x16_bf16 v[142:157], v[218:221], v[4:7], v[66:81]
	v_exp_f32_e32 v82, v82
	v_exp_f32_e32 v83, v83
	v_exp_f32_e32 v84, v84
	v_add_f32_e32 v27, v82, v83
	v_exp_f32_e32 v85, v85
	ds_read_b64_tr_b16 v[114:115], v2 offset:49152
	ds_read_b64_tr_b16 v[116:117], v2 offset:49664
	ds_read_b64_tr_b16 v[118:119], v2 offset:50176
	ds_read_b64_tr_b16 v[120:121], v2 offset:50688
	v_mfma_f32_32x32x16_bf16 v[158:173], v[214:217], v[4:7], v[66:81]
	v_exp_f32_e32 v86, v86
	v_add_f32_e32 v27, v27, v84
	v_exp_f32_e32 v87, v87
	v_add_f32_e32 v27, v27, v85
	v_exp_f32_e32 v88, v88
	ds_read_b64_tr_b16 v[122:123], v2 offset:51200
	ds_read_b64_tr_b16 v[124:125], v2 offset:51712
	ds_read_b64_tr_b16 v[126:127], v2 offset:52224
	ds_read_b64_tr_b16 v[128:129], v2 offset:52736
	v_mfma_f32_32x32x16_bf16 v[142:157], v[210:213], v[8:11], v[142:157]
	v_add_f32_e32 v27, v27, v86
	v_exp_f32_e32 v89, v89
	v_add_f32_e32 v27, v27, v87
	v_add_f32_e32 v27, v27, v88
	v_add_f32_e32 v27, v27, v89
	ds_read_b64_tr_b16 v[240:241], v2 offset:53248
	ds_read_b64_tr_b16 v[242:243], v2 offset:53760
	ds_read_b64_tr_b16 v[244:245], v2 offset:54272
	ds_read_b64_tr_b16 v[246:247], v2 offset:54784
	v_mfma_f32_32x32x16_bf16 v[158:173], v[206:209], v[8:11], v[158:173]
	v_cvt_pk_bf16_f32 v82, v82, v83
	v_cvt_pk_bf16_f32 v83, v84, v85
	v_cvt_pk_bf16_f32 v84, v86, v87
	v_cvt_pk_bf16_f32 v85, v88, v89
	ds_read_b64_tr_b16 v[248:249], v2 offset:55296
	ds_read_b64_tr_b16 v[250:251], v2 offset:55808
	ds_read_b64_tr_b16 v[20:21], v2 offset:56320
	ds_read_b64_tr_b16 v[22:23], v2 offset:56832
	v_mfma_f32_32x32x16_bf16 v[142:157], v[202:205], v[12:15], v[142:157]
	v_exp_f32_e32 v90, v90
	v_exp_f32_e32 v91, v91
	v_exp_f32_e32 v92, v92
	v_add_f32_e32 v27, v27, v90
	v_exp_f32_e32 v93, v93
	v_mfma_f32_32x32x16_bf16 v[158:173], v[198:201], v[12:15], v[158:173]
	v_add_f32_e32 v27, v27, v91
	v_exp_f32_e32 v94, v94
	v_add_f32_e32 v27, v27, v92
	v_exp_f32_e32 v95, v95
	v_add_f32_e32 v27, v27, v93
	s_waitcnt vmcnt(5)
	s_barrier
	v_mfma_f32_32x32x16_bf16 v[142:157], v[194:197], v[130:133], v[142:157]
	s_add_u32 m0, s57, 0x6000
	v_exp_f32_e32 v96, v96
	v_add_f32_e32 v27, v27, v94
	global_load_lds_dwordx4 v[28:29], off
	v_lshl_add_u64 v[28:29], v[28:29], 0, s[30:31]
	v_exp_f32_e32 v97, v97
	v_add_f32_e32 v27, v27, v95
	v_add_f32_e32 v27, v27, v96
	v_mfma_f32_32x32x16_bf16 v[158:173], v[190:193], v[130:133], v[158:173]
	s_add_u32 m0, s40, 0x3000
	v_add_f32_e32 v27, v27, v97
	v_cvt_pk_bf16_f32 v90, v90, v91
	global_load_lds_dwordx4 v[24:25], off
	v_lshl_add_u64 v[24:25], v[24:25], 0, s[30:31]
	v_cvt_pk_bf16_f32 v91, v92, v93
	v_cvt_pk_bf16_f32 v92, v94, v95
	v_cvt_pk_bf16_f32 v93, v96, v97
	v_mfma_f32_32x32x16_bf16 v[142:157], v[186:189], v[134:137], v[142:157]
	s_add_u32 m0, s43, 0x3000
	v_exp_f32_e32 v98, v98
	v_exp_f32_e32 v99, v99
	global_load_lds_dwordx4 v[30:31], off
	v_lshl_add_u64 v[30:31], v[30:31], 0, s[12:13]
	v_exp_f32_e32 v100, v100
	v_add_f32_e32 v27, v27, v98
	v_exp_f32_e32 v101, v101
	v_mfma_f32_32x32x16_bf16 v[158:173], v[182:185], v[134:137], v[158:173]
	v_add_f32_e32 v27, v27, v99
	v_exp_f32_e32 v102, v102
	v_add_f32_e32 v27, v27, v100
	v_exp_f32_e32 v103, v103
	v_add_f32_e32 v27, v27, v101
	v_mfma_f32_32x32x16_bf16 v[142:157], v[178:181], v[138:141], v[142:157]
	v_exp_f32_e32 v104, v104
	v_add_f32_e32 v27, v27, v102
	v_exp_f32_e32 v105, v105
	v_add_f32_e32 v27, v27, v103
	v_add_f32_e32 v27, v27, v104
	v_mfma_f32_32x32x16_bf16 v[158:173], v[174:177], v[138:141], v[158:173]
	v_add_f32_e32 v27, v27, v105
	v_cvt_pk_bf16_f32 v98, v98, v99
	v_cvt_pk_bf16_f32 v99, v100, v101
	v_cvt_pk_bf16_f32 v100, v102, v103
	v_cvt_pk_bf16_f32 v101, v104, v105
	s_waitcnt lgkmcnt(0)
	v_add_u32_e32 v2, 0x6000, v238
	v_mfma_f32_32x32x16_bf16 v[34:49], v[82:85], v[114:117], v[34:49]
	v_exp_f32_e32 v106, v106
	v_exp_f32_e32 v107, v107
	v_exp_f32_e32 v108, v108
	v_add_f32_e32 v27, v27, v106
	v_exp_f32_e32 v109, v109
	ds_read_b128 v[218:221], v2
	ds_read_b128 v[214:217], v2 offset:512
	ds_read_b128 v[210:213], v2 offset:2048
	v_mfma_f32_32x32x16_bf16 v[50:65], v[82:85], v[240:243], v[50:65]
	v_add_f32_e32 v27, v27, v107
	v_exp_f32_e32 v110, v110
	v_add_f32_e32 v27, v27, v108
	v_exp_f32_e32 v111, v111
	v_add_f32_e32 v27, v27, v109
	ds_read_b128 v[206:209], v2 offset:2560
	ds_read_b128 v[202:205], v2 offset:4096
	ds_read_b128 v[198:201], v2 offset:4608
	v_mfma_f32_32x32x16_bf16 v[34:49], v[90:93], v[118:121], v[34:49]
	v_exp_f32_e32 v112, v112
	v_add_f32_e32 v27, v27, v110
	v_exp_f32_e32 v113, v113
	v_add_f32_e32 v27, v27, v111
	v_add_f32_e32 v27, v27, v112
	ds_read_b128 v[194:197], v2 offset:6144
	ds_read_b128 v[190:193], v2 offset:6656
	ds_read_b128 v[186:189], v2 offset:8192
	v_mfma_f32_32x32x16_bf16 v[50:65], v[90:93], v[244:247], v[50:65]
	v_add_f32_e32 v27, v27, v113
	v_cvt_pk_bf16_f32 v106, v106, v107
	v_cvt_pk_bf16_f32 v107, v108, v109
	v_cvt_pk_bf16_f32 v108, v110, v111
	v_cvt_pk_bf16_f32 v109, v112, v113
	v_add_f32_e32 v236, v236, v27
	ds_read_b128 v[182:185], v2 offset:8704
	ds_read_b128 v[178:181], v2 offset:10240
	ds_read_b128 v[174:177], v2 offset:10752
	v_mfma_f32_32x32x16_bf16 v[34:49], v[98:101], v[122:125], v[34:49]
	v_max3_f32 v19, v142, v143, v144
	v_max3_f32 v26, v145, v146, v147
	v_max3_f32 v19, v19, v148, v149
	v_max3_f32 v26, v26, v150, v151
	v_mfma_f32_32x32x16_bf16 v[50:65], v[98:101], v[248:251], v[50:65]
	v_max3_f32 v19, v19, v152, v153
	v_max3_f32 v26, v26, v154, v155
	v_max3_f32 v19, v19, v156, v157
	v_max3_f32 v26, v26, v158, v159
	v_mfma_f32_32x32x16_bf16 v[34:49], v[106:109], v[126:129], v[34:49]
	v_max3_f32 v19, v19, v160, v161
	v_max3_f32 v26, v26, v162, v163
	v_max3_f32 v19, v19, v164, v165
	v_max3_f32 v26, v26, v166, v167
	v_mfma_f32_32x32x16_bf16 v[50:65], v[106:109], v[20:23], v[50:65]
	v_max3_f32 v19, v19, v168, v169
	v_max3_f32 v26, v26, v170, v171
	v_max3_f32 v19, v19, v172, v173
	v_max_f32_e32 v19, v19, v26
	v_cmp_lt_f32_e32 vcc, s41, v19
	s_cbranch_vccz .Lmy_nors_7
	s_nop 15
	s_nop 15
	v_mov_b32_e32 v26, v19
	s_nop 1
	v_permlane32_swap_b32_e32 v19, v26
	v_max_f32_e32 v19, v19, v26
	v_max_f32_e32 v19, v19, v19
	v_max_f32_e32 v90, 0, v19
	v_exp_f32_e64 v91, -v90
	v_add_f32_e32 v239, v239, v90
	v_xor_b32_e32 v66, 0x80000000, v239
	v_mov_b32_e32 v67, v66
	v_mov_b32_e32 v68, v66
	v_mov_b32_e32 v69, v66
	v_mov_b32_e32 v70, v66
	v_mov_b32_e32 v71, v66
	v_mov_b32_e32 v72, v66
	v_mov_b32_e32 v73, v66
	v_mov_b32_e32 v74, v66
	v_mov_b32_e32 v75, v66
	v_mov_b32_e32 v76, v66
	v_mov_b32_e32 v77, v66
	v_mov_b32_e32 v78, v66
	v_mov_b32_e32 v79, v66
	v_mov_b32_e32 v80, v66
	v_mov_b32_e32 v81, v66
	v_sub_f32_e32 v142, v142, v90
	v_sub_f32_e32 v143, v143, v90
	v_sub_f32_e32 v144, v144, v90
	v_sub_f32_e32 v145, v145, v90
	v_sub_f32_e32 v146, v146, v90
	v_sub_f32_e32 v147, v147, v90
	v_sub_f32_e32 v148, v148, v90
	v_sub_f32_e32 v149, v149, v90
	v_sub_f32_e32 v150, v150, v90
	v_sub_f32_e32 v151, v151, v90
	v_sub_f32_e32 v152, v152, v90
	v_sub_f32_e32 v153, v153, v90
	v_sub_f32_e32 v154, v154, v90
	v_sub_f32_e32 v155, v155, v90
	v_sub_f32_e32 v156, v156, v90
	v_sub_f32_e32 v157, v157, v90
	v_sub_f32_e32 v158, v158, v90
	v_sub_f32_e32 v159, v159, v90
	v_sub_f32_e32 v160, v160, v90
	v_sub_f32_e32 v161, v161, v90
	v_sub_f32_e32 v162, v162, v90
	v_sub_f32_e32 v163, v163, v90
	v_sub_f32_e32 v164, v164, v90
	v_sub_f32_e32 v165, v165, v90
	v_sub_f32_e32 v166, v166, v90
	v_sub_f32_e32 v167, v167, v90
	v_sub_f32_e32 v168, v168, v90
	v_sub_f32_e32 v169, v169, v90
	v_sub_f32_e32 v170, v170, v90
	v_sub_f32_e32 v171, v171, v90
	v_sub_f32_e32 v172, v172, v90
	v_sub_f32_e32 v173, v173, v90
	v_mul_f32_e32 v236, v236, v91
	s_mov_b64 s[96:97], exec
	s_and_b64 exec, exec, s[8:9]
	ds_write_b32 v235, v91
	s_mov_b64 exec, s[96:97]
	v_lshl_add_u32 v2, v228, 4, s47
	ds_read_b128 v[94:97], v2 offset:0
	s_waitcnt lgkmcnt(0)
	v_mul_f32_e32 v34, v34, v94
	v_mul_f32_e32 v50, v50, v94
	v_mul_f32_e32 v35, v35, v95
	v_mul_f32_e32 v51, v51, v95
	v_mul_f32_e32 v36, v36, v96
	v_mul_f32_e32 v52, v52, v96
	v_mul_f32_e32 v37, v37, v97
	v_mul_f32_e32 v53, v53, v97
	ds_read_b128 v[94:97], v2 offset:32
	s_waitcnt lgkmcnt(0)
	v_mul_f32_e32 v38, v38, v94
	v_mul_f32_e32 v54, v54, v94
	v_mul_f32_e32 v39, v39, v95
	v_mul_f32_e32 v55, v55, v95
	v_mul_f32_e32 v40, v40, v96
	v_mul_f32_e32 v56, v56, v96
	v_mul_f32_e32 v41, v41, v97
	v_mul_f32_e32 v57, v57, v97
	ds_read_b128 v[94:97], v2 offset:64
	s_waitcnt lgkmcnt(0)
	v_mul_f32_e32 v42, v42, v94
	v_mul_f32_e32 v58, v58, v94
	v_mul_f32_e32 v43, v43, v95
	v_mul_f32_e32 v59, v59, v95
	v_mul_f32_e32 v44, v44, v96
	v_mul_f32_e32 v60, v60, v96
	v_mul_f32_e32 v45, v45, v97
	v_mul_f32_e32 v61, v61, v97
	ds_read_b128 v[94:97], v2 offset:96
	s_waitcnt lgkmcnt(0)
	v_mul_f32_e32 v46, v46, v94
	v_mul_f32_e32 v62, v62, v94
	v_mul_f32_e32 v47, v47, v95
	v_mul_f32_e32 v63, v63, v95
	v_mul_f32_e32 v48, v48, v96
	v_mul_f32_e32 v64, v64, v96
	v_mul_f32_e32 v49, v49, v97
	v_mul_f32_e32 v65, v65, v97

.Lmy_nors_31:
	s_waitcnt lgkmcnt(0)
	v_add_u32_e32 v2, 0x2000, v237
	v_mfma_f32_32x32x16_bf16 v[82:97], v[218:221], v[4:7], v[66:81]
	v_exp_f32_e32 v142, v142
	v_exp_f32_e32 v143, v143
	v_exp_f32_e32 v144, v144
	v_add_f32_e32 v27, v142, v143
	v_exp_f32_e32 v145, v145
	ds_read_b64_tr_b16 v[114:115], v2 offset:49152
	ds_read_b64_tr_b16 v[116:117], v2 offset:49664
	ds_read_b64_tr_b16 v[118:119], v2 offset:50176
	ds_read_b64_tr_b16 v[120:121], v2 offset:50688
	v_mfma_f32_32x32x16_bf16 v[98:113], v[214:217], v[4:7], v[66:81]
	v_exp_f32_e32 v146, v146
	v_add_f32_e32 v27, v27, v144
	v_exp_f32_e32 v147, v147
	v_add_f32_e32 v27, v27, v145
	v_exp_f32_e32 v148, v148
	ds_read_b64_tr_b16 v[122:123], v2 offset:51200
	ds_read_b64_tr_b16 v[124:125], v2 offset:51712
	ds_read_b64_tr_b16 v[126:127], v2 offset:52224
	ds_read_b64_tr_b16 v[128:129], v2 offset:52736
	v_mfma_f32_32x32x16_bf16 v[82:97], v[210:213], v[8:11], v[82:97]
	v_add_f32_e32 v27, v27, v146
	v_exp_f32_e32 v149, v149
	v_add_f32_e32 v27, v27, v147
	v_add_f32_e32 v27, v27, v148
	v_add_f32_e32 v27, v27, v149
	ds_read_b64_tr_b16 v[240:241], v2 offset:53248
	ds_read_b64_tr_b16 v[242:243], v2 offset:53760
	ds_read_b64_tr_b16 v[244:245], v2 offset:54272
	ds_read_b64_tr_b16 v[246:247], v2 offset:54784
	v_mfma_f32_32x32x16_bf16 v[98:113], v[206:209], v[8:11], v[98:113]
	v_cvt_pk_bf16_f32 v142, v142, v143
	v_cvt_pk_bf16_f32 v143, v144, v145
	v_cvt_pk_bf16_f32 v144, v146, v147
	v_cvt_pk_bf16_f32 v145, v148, v149
	ds_read_b64_tr_b16 v[248:249], v2 offset:55296
	ds_read_b64_tr_b16 v[250:251], v2 offset:55808
	ds_read_b64_tr_b16 v[20:21], v2 offset:56320
	ds_read_b64_tr_b16 v[22:23], v2 offset:56832
	v_mfma_f32_32x32x16_bf16 v[82:97], v[202:205], v[12:15], v[82:97]
	v_exp_f32_e32 v150, v150
	v_exp_f32_e32 v151, v151
	v_exp_f32_e32 v152, v152
	v_add_f32_e32 v27, v27, v150
	v_exp_f32_e32 v153, v153
	v_mfma_f32_32x32x16_bf16 v[98:113], v[198:201], v[12:15], v[98:113]
	v_add_f32_e32 v27, v27, v151
	v_exp_f32_e32 v154, v154
	v_add_f32_e32 v27, v27, v152
	v_exp_f32_e32 v155, v155
	v_add_f32_e32 v27, v27, v153
	s_waitcnt vmcnt(3)
	s_barrier
	v_mfma_f32_32x32x16_bf16 v[82:97], v[194:197], v[130:133], v[82:97]
	s_add_u32 m0, s57, 0x0
	v_exp_f32_e32 v156, v156
	v_add_f32_e32 v27, v27, v154
	global_load_lds_dwordx4 v[28:29], off
	v_lshl_add_u64 v[28:29], v[28:29], 0, s[30:31]
	v_exp_f32_e32 v157, v157
	v_add_f32_e32 v27, v27, v155
	v_add_f32_e32 v27, v27, v156
	v_mfma_f32_32x32x16_bf16 v[98:113], v[190:193], v[130:133], v[98:113]
	s_add_u32 m0, s40, 0x6000
	v_add_f32_e32 v27, v27, v157
	v_cvt_pk_bf16_f32 v150, v150, v151
	global_load_lds_dwordx4 v[24:25], off
	v_lshl_add_u64 v[24:25], v[24:25], 0, s[30:31]
	v_cvt_pk_bf16_f32 v151, v152, v153
	v_cvt_pk_bf16_f32 v152, v154, v155
	v_cvt_pk_bf16_f32 v153, v156, v157
	v_mfma_f32_32x32x16_bf16 v[82:97], v[186:189], v[134:137], v[82:97]
	v_exp_f32_e32 v158, v158
	v_exp_f32_e32 v159, v159
	v_exp_f32_e32 v160, v160
	v_add_f32_e32 v27, v27, v158
	v_exp_f32_e32 v161, v161
	v_mfma_f32_32x32x16_bf16 v[98:113], v[182:185], v[134:137], v[98:113]
	v_add_f32_e32 v27, v27, v159
	v_exp_f32_e32 v162, v162
	v_add_f32_e32 v27, v27, v160
	v_exp_f32_e32 v163, v163
	v_add_f32_e32 v27, v27, v161
	v_mfma_f32_32x32x16_bf16 v[82:97], v[178:181], v[138:141], v[82:97]
	v_exp_f32_e32 v164, v164
	v_add_f32_e32 v27, v27, v162
	v_exp_f32_e32 v165, v165
	v_add_f32_e32 v27, v27, v163
	v_add_f32_e32 v27, v27, v164
	v_mfma_f32_32x32x16_bf16 v[98:113], v[174:177], v[138:141], v[98:113]
	v_add_f32_e32 v27, v27, v165
	v_cvt_pk_bf16_f32 v158, v158, v159
	v_cvt_pk_bf16_f32 v159, v160, v161
	v_cvt_pk_bf16_f32 v160, v162, v163
	v_cvt_pk_bf16_f32 v161, v164, v165
	s_waitcnt lgkmcnt(0)
	v_add_u32_e32 v2, 0x9000, v238
	v_mfma_f32_32x32x16_bf16 v[34:49], v[142:145], v[114:117], v[34:49]
	v_exp_f32_e32 v166, v166
	v_exp_f32_e32 v167, v167
	v_exp_f32_e32 v168, v168
	v_add_f32_e32 v27, v27, v166
	v_exp_f32_e32 v169, v169
	ds_read_b128 v[218:221], v2
	ds_read_b128 v[214:217], v2 offset:512
	ds_read_b128 v[210:213], v2 offset:2048
	v_mfma_f32_32x32x16_bf16 v[50:65], v[142:145], v[240:243], v[50:65]
	v_add_f32_e32 v27, v27, v167
	v_exp_f32_e32 v170, v170
	v_add_f32_e32 v27, v27, v168
	v_exp_f32_e32 v171, v171
	v_add_f32_e32 v27, v27, v169
	ds_read_b128 v[206:209], v2 offset:2560
	ds_read_b128 v[202:205], v2 offset:4096
	ds_read_b128 v[198:201], v2 offset:4608
	v_mfma_f32_32x32x16_bf16 v[34:49], v[150:153], v[118:121], v[34:49]
	v_exp_f32_e32 v172, v172
	v_add_f32_e32 v27, v27, v170
	v_exp_f32_e32 v173, v173
	v_add_f32_e32 v27, v27, v171
	v_add_f32_e32 v27, v27, v172
	ds_read_b128 v[194:197], v2 offset:6144
	ds_read_b128 v[190:193], v2 offset:6656
	ds_read_b128 v[186:189], v2 offset:8192
	v_mfma_f32_32x32x16_bf16 v[50:65], v[150:153], v[244:247], v[50:65]
	v_add_f32_e32 v27, v27, v173
	v_cvt_pk_bf16_f32 v166, v166, v167
	v_cvt_pk_bf16_f32 v167, v168, v169
	v_cvt_pk_bf16_f32 v168, v170, v171
	v_cvt_pk_bf16_f32 v169, v172, v173
	v_add_f32_e32 v236, v236, v27
	ds_read_b128 v[182:185], v2 offset:8704
	ds_read_b128 v[178:181], v2 offset:10240
	ds_read_b128 v[174:177], v2 offset:10752
	v_mfma_f32_32x32x16_bf16 v[34:49], v[158:161], v[122:125], v[34:49]
	v_max3_f32 v19, v82, v83, v84
	v_max3_f32 v26, v85, v86, v87
	v_max3_f32 v19, v19, v88, v89
	v_max3_f32 v26, v26, v90, v91
	v_mfma_f32_32x32x16_bf16 v[50:65], v[158:161], v[248:251], v[50:65]
	v_max3_f32 v19, v19, v92, v93
	v_max3_f32 v26, v26, v94, v95
	v_max3_f32 v19, v19, v96, v97
	v_max3_f32 v26, v26, v98, v99
	v_mfma_f32_32x32x16_bf16 v[34:49], v[166:169], v[126:129], v[34:49]
	v_max3_f32 v19, v19, v100, v101
	v_max3_f32 v26, v26, v102, v103
	v_max3_f32 v19, v19, v104, v105
	v_max3_f32 v26, v26, v106, v107
	v_mfma_f32_32x32x16_bf16 v[50:65], v[166:169], v[20:23], v[50:65]
	v_max3_f32 v19, v19, v108, v109
	v_max3_f32 v26, v26, v110, v111
	v_max3_f32 v19, v19, v112, v113
	v_max_f32_e32 v19, v19, v26
	v_cmp_lt_f32_e32 vcc, s41, v19
	s_cbranch_vccz .Lmy_nors_32
	s_nop 15
	s_nop 15
	v_mov_b32_e32 v26, v19
	s_nop 1
	v_permlane32_swap_b32_e32 v19, v26
	v_max_f32_e32 v19, v19, v26
	v_max_f32_e32 v19, v19, v19
	v_max_f32_e32 v150, 0, v19
	v_exp_f32_e64 v151, -v150
	v_add_f32_e32 v239, v239, v150
	v_xor_b32_e32 v66, 0x80000000, v239
	v_mov_b32_e32 v67, v66
	v_mov_b32_e32 v68, v66
	v_mov_b32_e32 v69, v66
	v_mov_b32_e32 v70, v66
	v_mov_b32_e32 v71, v66
	v_mov_b32_e32 v72, v66
	v_mov_b32_e32 v73, v66
	v_mov_b32_e32 v74, v66
	v_mov_b32_e32 v75, v66
	v_mov_b32_e32 v76, v66
	v_mov_b32_e32 v77, v66
	v_mov_b32_e32 v78, v66
	v_mov_b32_e32 v79, v66
	v_mov_b32_e32 v80, v66
	v_mov_b32_e32 v81, v66
	v_sub_f32_e32 v82, v82, v150
	v_sub_f32_e32 v83, v83, v150
	v_sub_f32_e32 v84, v84, v150
	v_sub_f32_e32 v85, v85, v150
	v_sub_f32_e32 v86, v86, v150
	v_sub_f32_e32 v87, v87, v150
	v_sub_f32_e32 v88, v88, v150
	v_sub_f32_e32 v89, v89, v150
	v_sub_f32_e32 v90, v90, v150
	v_sub_f32_e32 v91, v91, v150
	v_sub_f32_e32 v92, v92, v150
	v_sub_f32_e32 v93, v93, v150
	v_sub_f32_e32 v94, v94, v150
	v_sub_f32_e32 v95, v95, v150
	v_sub_f32_e32 v96, v96, v150
	v_sub_f32_e32 v97, v97, v150
	v_sub_f32_e32 v98, v98, v150
	v_sub_f32_e32 v99, v99, v150
	v_sub_f32_e32 v100, v100, v150
	v_sub_f32_e32 v101, v101, v150
	v_sub_f32_e32 v102, v102, v150
	v_sub_f32_e32 v103, v103, v150
	v_sub_f32_e32 v104, v104, v150
	v_sub_f32_e32 v105, v105, v150
	v_sub_f32_e32 v106, v106, v150
	v_sub_f32_e32 v107, v107, v150
	v_sub_f32_e32 v108, v108, v150
	v_sub_f32_e32 v109, v109, v150
	v_sub_f32_e32 v110, v110, v150
	v_sub_f32_e32 v111, v111, v150
	v_sub_f32_e32 v112, v112, v150
	v_sub_f32_e32 v113, v113, v150
	v_mul_f32_e32 v236, v236, v151
	s_mov_b64 s[96:97], exec
	s_and_b64 exec, exec, s[8:9]
	ds_write_b32 v235, v151
	s_mov_b64 exec, s[96:97]
	v_lshl_add_u32 v2, v228, 4, s47
	ds_read_b128 v[154:157], v2 offset:0
	s_waitcnt lgkmcnt(0)
	v_mul_f32_e32 v34, v34, v154
	v_mul_f32_e32 v50, v50, v154
	v_mul_f32_e32 v35, v35, v155
	v_mul_f32_e32 v51, v51, v155
	v_mul_f32_e32 v36, v36, v156
	v_mul_f32_e32 v52, v52, v156
	v_mul_f32_e32 v37, v37, v157
	v_mul_f32_e32 v53, v53, v157
	ds_read_b128 v[154:157], v2 offset:32
	s_waitcnt lgkmcnt(0)
	v_mul_f32_e32 v38, v38, v154
	v_mul_f32_e32 v54, v54, v154
	v_mul_f32_e32 v39, v39, v155
	v_mul_f32_e32 v55, v55, v155
	v_mul_f32_e32 v40, v40, v156
	v_mul_f32_e32 v56, v56, v156
	v_mul_f32_e32 v41, v41, v157
	v_mul_f32_e32 v57, v57, v157
	ds_read_b128 v[154:157], v2 offset:64
	s_waitcnt lgkmcnt(0)
	v_mul_f32_e32 v42, v42, v154
	v_mul_f32_e32 v58, v58, v154
	v_mul_f32_e32 v43, v43, v155
	v_mul_f32_e32 v59, v59, v155
	v_mul_f32_e32 v44, v44, v156
	v_mul_f32_e32 v60, v60, v156
	v_mul_f32_e32 v45, v45, v157
	v_mul_f32_e32 v61, v61, v157
	ds_read_b128 v[154:157], v2 offset:96
	s_waitcnt lgkmcnt(0)
	v_mul_f32_e32 v46, v46, v154
	v_mul_f32_e32 v62, v62, v154
	v_mul_f32_e32 v47, v47, v155
	v_mul_f32_e32 v63, v63, v155
	v_mul_f32_e32 v48, v48, v156
	v_mul_f32_e32 v64, v64, v156
	v_mul_f32_e32 v49, v49, v157
	v_mul_f32_e32 v65, v65, v157

.Lmy_nors_33:
	s_waitcnt lgkmcnt(0)
	v_add_u32_e32 v2, 0x6000, v237
	v_mfma_f32_32x32x16_bf16 v[82:97], v[218:221], v[4:7], v[66:81]
	v_exp_f32_e32 v142, v142
	v_exp_f32_e32 v143, v143
	v_exp_f32_e32 v144, v144
	v_add_f32_e32 v27, v142, v143
	v_exp_f32_e32 v145, v145
	ds_read_b64_tr_b16 v[114:115], v2 offset:49152
	ds_read_b64_tr_b16 v[116:117], v2 offset:49664
	ds_read_b64_tr_b16 v[118:119], v2 offset:50176
	ds_read_b64_tr_b16 v[120:121], v2 offset:50688
	v_mfma_f32_32x32x16_bf16 v[98:113], v[214:217], v[4:7], v[66:81]
	v_exp_f32_e32 v146, v146
	v_add_f32_e32 v27, v27, v144
	v_exp_f32_e32 v147, v147
	v_add_f32_e32 v27, v27, v145
	v_exp_f32_e32 v148, v148
	ds_read_b64_tr_b16 v[122:123], v2 offset:51200
	ds_read_b64_tr_b16 v[124:125], v2 offset:51712
	ds_read_b64_tr_b16 v[126:127], v2 offset:52224
	ds_read_b64_tr_b16 v[128:129], v2 offset:52736
	v_mfma_f32_32x32x16_bf16 v[82:97], v[210:213], v[8:11], v[82:97]
	v_add_f32_e32 v27, v27, v146
	v_exp_f32_e32 v149, v149
	v_add_f32_e32 v27, v27, v147
	v_add_f32_e32 v27, v27, v148
	v_add_f32_e32 v27, v27, v149
	ds_read_b64_tr_b16 v[240:241], v2 offset:53248
	ds_read_b64_tr_b16 v[242:243], v2 offset:53760
	ds_read_b64_tr_b16 v[244:245], v2 offset:54272
	ds_read_b64_tr_b16 v[246:247], v2 offset:54784
	v_mfma_f32_32x32x16_bf16 v[98:113], v[206:209], v[8:11], v[98:113]
	v_cvt_pk_bf16_f32 v142, v142, v143
	v_cvt_pk_bf16_f32 v143, v144, v145
	v_cvt_pk_bf16_f32 v144, v146, v147
	v_cvt_pk_bf16_f32 v145, v148, v149
	ds_read_b64_tr_b16 v[248:249], v2 offset:55296
	ds_read_b64_tr_b16 v[250:251], v2 offset:55808
	ds_read_b64_tr_b16 v[20:21], v2 offset:56320
	ds_read_b64_tr_b16 v[22:23], v2 offset:56832
	v_mfma_f32_32x32x16_bf16 v[82:97], v[202:205], v[12:15], v[82:97]
	v_exp_f32_e32 v150, v150
	v_exp_f32_e32 v151, v151
	v_exp_f32_e32 v152, v152
	v_add_f32_e32 v27, v27, v150
	v_exp_f32_e32 v153, v153
	v_mfma_f32_32x32x16_bf16 v[98:113], v[198:201], v[12:15], v[98:113]
	v_add_f32_e32 v27, v27, v151
	v_exp_f32_e32 v154, v154
	v_add_f32_e32 v27, v27, v152
	v_exp_f32_e32 v155, v155
	v_add_f32_e32 v27, v27, v153
	s_waitcnt vmcnt(3)
	s_barrier
	v_mfma_f32_32x32x16_bf16 v[82:97], v[194:197], v[130:133], v[82:97]
	s_add_u32 m0, s57, 0x4000
	v_exp_f32_e32 v156, v156
	v_add_f32_e32 v27, v27, v154
	global_load_lds_dwordx4 v[28:29], off
	v_lshl_add_u64 v[28:29], v[28:29], 0, s[30:31]
	v_exp_f32_e32 v157, v157
	v_add_f32_e32 v27, v27, v155
	v_add_f32_e32 v27, v27, v156
	v_mfma_f32_32x32x16_bf16 v[98:113], v[190:193], v[130:133], v[98:113]
	s_cmp_eq_u32 s79, 1
	s_cbranch_scc1 .Lmy_gl_34
	s_add_u32 m0, s40, 0x0
	s_nop 0
	global_load_lds_dwordx4 v[24:25], off
	v_lshl_add_u64 v[24:25], v[24:25], 0, s[30:31]

.Lmy_B_loop:
	s_waitcnt lgkmcnt(0)
	v_mov_b32_e32 v2, v237
	v_mfma_f32_32x32x16_bf16 v[142:157], v[218:221], v[4:7], v[66:81]
	v_exp_f32_e32 v82, v82
	v_exp_f32_e32 v83, v83
	v_exp_f32_e32 v84, v84
	v_add_f32_e32 v27, v82, v83
	v_exp_f32_e32 v85, v85
	ds_read_b64_tr_b16 v[114:115], v2 offset:49152
	ds_read_b64_tr_b16 v[116:117], v2 offset:49664
	ds_read_b64_tr_b16 v[118:119], v2 offset:50176
	ds_read_b64_tr_b16 v[120:121], v2 offset:50688
	v_mfma_f32_32x32x16_bf16 v[158:173], v[214:217], v[4:7], v[66:81]
	v_exp_f32_e32 v86, v86
	v_add_f32_e32 v27, v27, v84
	v_exp_f32_e32 v87, v87
	v_add_f32_e32 v27, v27, v85
	v_exp_f32_e32 v88, v88
	ds_read_b64_tr_b16 v[122:123], v2 offset:51200
	ds_read_b64_tr_b16 v[124:125], v2 offset:51712
	ds_read_b64_tr_b16 v[126:127], v2 offset:52224
	ds_read_b64_tr_b16 v[128:129], v2 offset:52736
	v_mfma_f32_32x32x16_bf16 v[142:157], v[210:213], v[8:11], v[142:157]
	v_add_f32_e32 v27, v27, v86
	v_exp_f32_e32 v89, v89
	v_add_f32_e32 v27, v27, v87
	v_add_f32_e32 v27, v27, v88
	v_add_f32_e32 v27, v27, v89
	ds_read_b64_tr_b16 v[240:241], v2 offset:53248
	ds_read_b64_tr_b16 v[242:243], v2 offset:53760
	ds_read_b64_tr_b16 v[244:245], v2 offset:54272
	ds_read_b64_tr_b16 v[246:247], v2 offset:54784
	v_mfma_f32_32x32x16_bf16 v[158:173], v[206:209], v[8:11], v[158:173]
	v_cvt_pk_bf16_f32 v82, v82, v83
	v_cvt_pk_bf16_f32 v83, v84, v85
	v_cvt_pk_bf16_f32 v84, v86, v87
	v_cvt_pk_bf16_f32 v85, v88, v89
	ds_read_b64_tr_b16 v[248:249], v2 offset:55296
	ds_read_b64_tr_b16 v[250:251], v2 offset:55808
	ds_read_b64_tr_b16 v[20:21], v2 offset:56320
	ds_read_b64_tr_b16 v[22:23], v2 offset:56832
	v_mfma_f32_32x32x16_bf16 v[142:157], v[202:205], v[12:15], v[142:157]
	v_exp_f32_e32 v90, v90
	v_exp_f32_e32 v91, v91
	v_exp_f32_e32 v92, v92
	v_add_f32_e32 v27, v27, v90
	v_exp_f32_e32 v93, v93
	v_mfma_f32_32x32x16_bf16 v[158:173], v[198:201], v[12:15], v[158:173]
	v_add_f32_e32 v27, v27, v91
	v_exp_f32_e32 v94, v94
	v_add_f32_e32 v27, v27, v92
	v_exp_f32_e32 v95, v95
	v_add_f32_e32 v27, v27, v93
	s_waitcnt vmcnt(3)
	s_barrier
	v_mfma_f32_32x32x16_bf16 v[142:157], v[194:197], v[130:133], v[142:157]
	s_add_u32 m0, s57, 0x6000
	v_exp_f32_e32 v96, v96
	v_add_f32_e32 v27, v27, v94
	global_load_lds_dwordx4 v[28:29], off
	v_lshl_add_u64 v[28:29], v[28:29], 0, s[30:31]
	v_exp_f32_e32 v97, v97
	v_add_f32_e32 v27, v27, v95
	v_add_f32_e32 v27, v27, v96
	v_mfma_f32_32x32x16_bf16 v[158:173], v[190:193], v[130:133], v[158:173]
	s_add_u32 m0, s40, 0x3000
	v_add_f32_e32 v27, v27, v97
	v_cvt_pk_bf16_f32 v90, v90, v91
	global_load_lds_dwordx4 v[24:25], off
	v_lshl_add_u64 v[24:25], v[24:25], 0, s[30:31]
	v_cvt_pk_bf16_f32 v91, v92, v93
	v_cvt_pk_bf16_f32 v92, v94, v95
	v_cvt_pk_bf16_f32 v93, v96, v97
	v_mfma_f32_32x32x16_bf16 v[142:157], v[186:189], v[134:137], v[142:157]
	v_exp_f32_e32 v98, v98
	v_exp_f32_e32 v99, v99
	v_exp_f32_e32 v100, v100
	v_add_f32_e32 v27, v27, v98
	v_exp_f32_e32 v101, v101
	v_mfma_f32_32x32x16_bf16 v[158:173], v[182:185], v[134:137], v[158:173]
	v_add_f32_e32 v27, v27, v99
	v_exp_f32_e32 v102, v102
	v_add_f32_e32 v27, v27, v100
	v_exp_f32_e32 v103, v103
	v_add_f32_e32 v27, v27, v101
	v_mfma_f32_32x32x16_bf16 v[142:157], v[178:181], v[138:141], v[142:157]
	v_exp_f32_e32 v104, v104
	v_add_f32_e32 v27, v27, v102
	v_exp_f32_e32 v105, v105
	v_add_f32_e32 v27, v27, v103
	v_add_f32_e32 v27, v27, v104
	v_mfma_f32_32x32x16_bf16 v[158:173], v[174:177], v[138:141], v[158:173]
	v_add_f32_e32 v27, v27, v105
	v_cvt_pk_bf16_f32 v98, v98, v99
	v_cvt_pk_bf16_f32 v99, v100, v101
	v_cvt_pk_bf16_f32 v100, v102, v103
	v_cvt_pk_bf16_f32 v101, v104, v105
	s_waitcnt lgkmcnt(0)
	v_add_u32_e32 v2, 0x6000, v238
	v_mfma_f32_32x32x16_bf16 v[34:49], v[82:85], v[114:117], v[34:49]
	v_exp_f32_e32 v106, v106
	v_exp_f32_e32 v107, v107
	v_exp_f32_e32 v108, v108
	v_add_f32_e32 v27, v27, v106
	v_exp_f32_e32 v109, v109
	ds_read_b128 v[218:221], v2
	ds_read_b128 v[214:217], v2 offset:512
	ds_read_b128 v[210:213], v2 offset:2048
	v_mfma_f32_32x32x16_bf16 v[50:65], v[82:85], v[240:243], v[50:65]
	v_add_f32_e32 v27, v27, v107
	v_exp_f32_e32 v110, v110
	v_add_f32_e32 v27, v27, v108
	v_exp_f32_e32 v111, v111
	v_add_f32_e32 v27, v27, v109
	ds_read_b128 v[206:209], v2 offset:2560
	ds_read_b128 v[202:205], v2 offset:4096
	ds_read_b128 v[198:201], v2 offset:4608
	v_mfma_f32_32x32x16_bf16 v[34:49], v[90:93], v[118:121], v[34:49]
	v_exp_f32_e32 v112, v112
	v_add_f32_e32 v27, v27, v110
	v_exp_f32_e32 v113, v113
	v_add_f32_e32 v27, v27, v111
	v_add_f32_e32 v27, v27, v112
	ds_read_b128 v[194:197], v2 offset:6144
	ds_read_b128 v[190:193], v2 offset:6656
	ds_read_b128 v[186:189], v2 offset:8192
	v_mfma_f32_32x32x16_bf16 v[50:65], v[90:93], v[244:247], v[50:65]
	v_add_f32_e32 v27, v27, v113
	v_cvt_pk_bf16_f32 v106, v106, v107
	v_cvt_pk_bf16_f32 v107, v108, v109
	v_cvt_pk_bf16_f32 v108, v110, v111
	v_cvt_pk_bf16_f32 v109, v112, v113
	v_add_f32_e32 v236, v236, v27
	ds_read_b128 v[182:185], v2 offset:8704
	ds_read_b128 v[178:181], v2 offset:10240
	ds_read_b128 v[174:177], v2 offset:10752
	v_mfma_f32_32x32x16_bf16 v[34:49], v[98:101], v[122:125], v[34:49]
	v_max3_f32 v19, v142, v143, v144
	v_max3_f32 v26, v145, v146, v147
	v_max3_f32 v19, v19, v148, v149
	v_max3_f32 v26, v26, v150, v151
	v_mfma_f32_32x32x16_bf16 v[50:65], v[98:101], v[248:251], v[50:65]
	v_max3_f32 v19, v19, v152, v153
	v_max3_f32 v26, v26, v154, v155
	v_max3_f32 v19, v19, v156, v157
	v_max3_f32 v26, v26, v158, v159
	v_mfma_f32_32x32x16_bf16 v[34:49], v[106:109], v[126:129], v[34:49]
	v_max3_f32 v19, v19, v160, v161
	v_max3_f32 v26, v26, v162, v163
	v_max3_f32 v19, v19, v164, v165
	v_max3_f32 v26, v26, v166, v167
	v_mfma_f32_32x32x16_bf16 v[50:65], v[106:109], v[20:23], v[50:65]
	v_max3_f32 v19, v19, v168, v169
	v_max3_f32 v26, v26, v170, v171
	v_max3_f32 v19, v19, v172, v173
	v_max_f32_e32 v19, v19, v26
	v_cmp_lt_f32_e32 vcc, s41, v19
	s_cbranch_vccz .Lmy_nors_36
	s_nop 15
	s_nop 15
	v_mov_b32_e32 v26, v19
	s_nop 1
	v_permlane32_swap_b32_e32 v19, v26
	v_max_f32_e32 v19, v19, v26
	v_max_f32_e32 v19, v19, v19
	v_max_f32_e32 v90, 0, v19
	v_exp_f32_e64 v91, -v90
	v_add_f32_e32 v239, v239, v90
	v_xor_b32_e32 v66, 0x80000000, v239
	v_mov_b32_e32 v67, v66
	v_mov_b32_e32 v68, v66
	v_mov_b32_e32 v69, v66
	v_mov_b32_e32 v70, v66
	v_mov_b32_e32 v71, v66
	v_mov_b32_e32 v72, v66
	v_mov_b32_e32 v73, v66
	v_mov_b32_e32 v74, v66
	v_mov_b32_e32 v75, v66
	v_mov_b32_e32 v76, v66
	v_mov_b32_e32 v77, v66
	v_mov_b32_e32 v78, v66
	v_mov_b32_e32 v79, v66
	v_mov_b32_e32 v80, v66
	v_mov_b32_e32 v81, v66
	v_sub_f32_e32 v142, v142, v90
	v_sub_f32_e32 v143, v143, v90
	v_sub_f32_e32 v144, v144, v90
	v_sub_f32_e32 v145, v145, v90
	v_sub_f32_e32 v146, v146, v90
	v_sub_f32_e32 v147, v147, v90
	v_sub_f32_e32 v148, v148, v90
	v_sub_f32_e32 v149, v149, v90
	v_sub_f32_e32 v150, v150, v90
	v_sub_f32_e32 v151, v151, v90
	v_sub_f32_e32 v152, v152, v90
	v_sub_f32_e32 v153, v153, v90
	v_sub_f32_e32 v154, v154, v90
	v_sub_f32_e32 v155, v155, v90
	v_sub_f32_e32 v156, v156, v90
	v_sub_f32_e32 v157, v157, v90
	v_sub_f32_e32 v158, v158, v90
	v_sub_f32_e32 v159, v159, v90
	v_sub_f32_e32 v160, v160, v90
	v_sub_f32_e32 v161, v161, v90
	v_sub_f32_e32 v162, v162, v90
	v_sub_f32_e32 v163, v163, v90
	v_sub_f32_e32 v164, v164, v90
	v_sub_f32_e32 v165, v165, v90
	v_sub_f32_e32 v166, v166, v90
	v_sub_f32_e32 v167, v167, v90
	v_sub_f32_e32 v168, v168, v90
	v_sub_f32_e32 v169, v169, v90
	v_sub_f32_e32 v170, v170, v90
	v_sub_f32_e32 v171, v171, v90
	v_sub_f32_e32 v172, v172, v90
	v_sub_f32_e32 v173, v173, v90
	v_mul_f32_e32 v236, v236, v91
	s_mov_b64 s[96:97], exec
	s_and_b64 exec, exec, s[8:9]
	ds_write_b32 v235, v91
	s_mov_b64 exec, s[96:97]
	v_lshl_add_u32 v2, v228, 4, s47
	ds_read_b128 v[94:97], v2 offset:0
	s_waitcnt lgkmcnt(0)
	v_mul_f32_e32 v34, v34, v94
	v_mul_f32_e32 v50, v50, v94
	v_mul_f32_e32 v35, v35, v95
	v_mul_f32_e32 v51, v51, v95
	v_mul_f32_e32 v36, v36, v96
	v_mul_f32_e32 v52, v52, v96
	v_mul_f32_e32 v37, v37, v97
	v_mul_f32_e32 v53, v53, v97
	ds_read_b128 v[94:97], v2 offset:32
	s_waitcnt lgkmcnt(0)
	v_mul_f32_e32 v38, v38, v94
	v_mul_f32_e32 v54, v54, v94
	v_mul_f32_e32 v39, v39, v95
	v_mul_f32_e32 v55, v55, v95
	v_mul_f32_e32 v40, v40, v96
	v_mul_f32_e32 v56, v56, v96
	v_mul_f32_e32 v41, v41, v97
	v_mul_f32_e32 v57, v57, v97
	ds_read_b128 v[94:97], v2 offset:64
	s_waitcnt lgkmcnt(0)
	v_mul_f32_e32 v42, v42, v94
	v_mul_f32_e32 v58, v58, v94
	v_mul_f32_e32 v43, v43, v95
	v_mul_f32_e32 v59, v59, v95
	v_mul_f32_e32 v44, v44, v96
	v_mul_f32_e32 v60, v60, v96
	v_mul_f32_e32 v45, v45, v97
	v_mul_f32_e32 v61, v61, v97
	ds_read_b128 v[94:97], v2 offset:96
	s_waitcnt lgkmcnt(0)
	v_mul_f32_e32 v46, v46, v94
	v_mul_f32_e32 v62, v62, v94
	v_mul_f32_e32 v47, v47, v95
	v_mul_f32_e32 v63, v63, v95
	v_mul_f32_e32 v48, v48, v96
	v_mul_f32_e32 v64, v64, v96
	v_mul_f32_e32 v49, v49, v97
	v_mul_f32_e32 v65, v65, v97
